# z-GEMM K-loop: LDS-DMA loads use scalar base + 32-bit lane offset (16 fewer 64-bit VALU adds per iteration)
# speedup vs baseline: 1.0127x; 1.0039x over previous
; #define PG8_STAGE(bufoff, gbase, voff) do { unsigned long long _gb = (unsigned long long)(gbase); asm volatile("" : "+s"(_gb)); _Pragma("unroll") for (int _i = 0; _i < 2; ++_i) \
;         __builtin_amdgcn_global_load_lds((const GAS unsigned*)((const GAS char*)_gb + (voff)[_i]), (LAS unsigned*)(lds + (bufoff) + ldsw + _i * 8192), 16, 0, 0); } while (0)
; #define PG8_LDA(dst, b, h) do { _Pragma("unroll") for (int m = 0; m < 4; ++m) _Pragma("unroll") for (int k = 0; k < 2; ++k) dst[m][k] = *(const LAS bf16x8*)(lds + PG8_SA(b, h) + aoff + m * 2048 + k * 1024); } while (0)
; #define PG8_LDB(dst, b, h) do { _Pragma("unroll") for (int n = 0; n < 2; ++n) _Pragma("unroll") for (int k = 0; k < 2; ++k) dst[n][k] = *(const LAS bf16x8*)(lds + PG8_SB(b, h) + boff + n * 2048 + k * 1024); } while (0)
; #define PG8_WAIT_V(n) asm volatile("s_waitcnt vmcnt(" #n ")" ::: "memory")
; #define PG8_WAIT_L(n) asm volatile("s_waitcnt lgkmcnt(" #n ")" ::: "memory")
; #define PG8_BAR __builtin_amdgcn_s_barrier()
; #define PG8_SCHED __builtin_amdgcn_sched_barrier(0)
; template <class Epi, bool ALIGN_EPI>
; __device__ __forceinline__ void gemm_phase(LAS unsigned char* lds, const Gemm g, const StaticOrder& S, const Epi& E, const int wid) {
;     ...
;         for (int t = 0; t < nt; t += 2) {
;             const bool last = (t == nt - 2);
;             const char* a1 = cA + (size_t)(t + 1) * kstep;
;             const char* a2 = last ? nA : cA + (size_t)(t + 2) * kstep; const char* b2 = last ? nB : cB + (size_t)(t + 2) * kstep;
;             const char* a3 = a2 + kstep; const char* b3 = b2 + kstep;
;             PG8_LDB(B0, 0, 0); PG8_LDB(B1, 0, 1); PG8_SCHED; PG8_LDA(At, 0, 0); PG8_STAGE(PG8_SA(1, 1), a1 + hstep, voffA);
;             PG8_WAIT_V(8); PG8_WAIT_L(0); PG8_BAR; PG8_MMA(0, 0, At, B0); PG8_MMA(0, 1, At, B1); PG8_BAR; PG8_SCHED;
;             PG8_LDA(At, 0, 1); PG8_STAGE(PG8_SB(0, 0), b2, voffB); PG8_STAGE(PG8_SB(0, 1), b2 + hstepB, voffB); PG8_STAGE(PG8_SA(0, 0), a2, voffA);
;             PG8_WAIT_V(8); PG8_WAIT_L(0); PG8_BAR; PG8_MMA(1, 0, At, B0); PG8_MMA(1, 1, At, B1); PG8_BAR; PG8_SCHED;
;             PG8_LDB(B0, 1, 0); PG8_LDB(B1, 1, 1); PG8_SCHED; PG8_LDA(At, 1, 0); PG8_STAGE(PG8_SA(0, 1), a2 + hstep, voffA);
;             PG8_WAIT_V(8); PG8_WAIT_L(0); PG8_BAR; PG8_MMA(0, 0, At, B0); PG8_MMA(0, 1, At, B1); PG8_BAR; PG8_SCHED;
.LBB0_105:
	ds_read_b128 v[128:131], v204
	ds_read_b128 v[132:135], v204 offset:1024
	ds_read_b128 v[136:139], v204 offset:2048
	ds_read_b128 v[140:143], v204 offset:3072
	ds_read_b128 v[162:165], v205
	ds_read_b128 v[166:169], v205 offset:1024
	ds_read_b128 v[170:173], v205 offset:2048
	ds_read_b128 v[174:177], v205 offset:3072
	s_add_u32 s6, s2, 0x100
	s_addc_u32 s7, s3, 0
	s_cmp_eq_u32 s74, 28
	s_cselect_b32 s52, s70, s6
	s_cselect_b32 s53, s39, s7
	s_cselect_b32 s50, s71, s72
	s_cselect_b32 s51, s37, s73
	s_add_u32 s48, s52, 0x80
	s_addc_u32 s49, s53, 0
	s_add_u32 s2, s2, 0x80080
	s_addc_u32 s3, s3, 0
	ds_read_b128 v[178:181], v206
	ds_read_b128 v[186:189], v206 offset:1024
	ds_read_b128 v[190:193], v206 offset:2048
	ds_read_b128 v[194:197], v206 offset:3072
	ds_read_b128 v[198:201], v206 offset:4096
	ds_read_b128 v[210:213], v206 offset:5120
	ds_read_b128 v[214:217], v206 offset:6144
	ds_read_b128 v[218:221], v206 offset:7168
	s_add_i32 m0, s45, 0xc000
	s_nop 0
	global_load_lds_dwordx4 v144, s[2:3]
	s_add_i32 m0, s45, 0xe000
	s_nop 0
	global_load_lds_dwordx4 v148, s[2:3]
	s_waitcnt vmcnt(8)
	s_waitcnt lgkmcnt(0)
	s_barrier
	s_setprio 1
	v_mfma_f32_16x16x32_bf16 v[124:127], v[128:131], v[178:181], v[124:127]
	v_mfma_f32_16x16x32_bf16 v[120:123], v[136:139], v[178:181], v[120:123]
	v_mfma_f32_16x16x32_bf16 v[108:111], v[128:131], v[190:193], v[108:111]
	v_mfma_f32_16x16x32_bf16 v[104:107], v[136:139], v[190:193], v[104:107]
	v_mfma_f32_16x16x32_bf16 v[92:95], v[128:131], v[198:201], v[92:95]
	v_mfma_f32_16x16x32_bf16 v[88:91], v[136:139], v[198:201], v[88:91]
	v_mfma_f32_16x16x32_bf16 v[76:79], v[128:131], v[214:217], v[76:79]
	v_mfma_f32_16x16x32_bf16 v[72:75], v[136:139], v[214:217], v[72:75]
	v_mfma_f32_16x16x32_bf16 v[124:127], v[132:135], v[186:189], v[124:127]
	v_mfma_f32_16x16x32_bf16 v[120:123], v[140:143], v[186:189], v[120:123]
	v_mfma_f32_16x16x32_bf16 v[108:111], v[132:135], v[194:197], v[108:111]
	v_mfma_f32_16x16x32_bf16 v[104:107], v[140:143], v[194:197], v[104:107]
	v_mfma_f32_16x16x32_bf16 v[92:95], v[132:135], v[210:213], v[92:95]
	v_mfma_f32_16x16x32_bf16 v[88:91], v[140:143], v[210:213], v[88:91]
	v_mfma_f32_16x16x32_bf16 v[76:79], v[132:135], v[218:221], v[76:79]
	v_mfma_f32_16x16x32_bf16 v[72:75], v[140:143], v[218:221], v[72:75]
	v_mfma_f32_16x16x32_bf16 v[116:119], v[162:165], v[178:181], v[116:119]
	v_mfma_f32_16x16x32_bf16 v[112:115], v[170:173], v[178:181], v[112:115]
	v_mfma_f32_16x16x32_bf16 v[100:103], v[162:165], v[190:193], v[100:103]
	v_mfma_f32_16x16x32_bf16 v[96:99], v[170:173], v[190:193], v[96:99]
	v_mfma_f32_16x16x32_bf16 v[84:87], v[162:165], v[198:201], v[84:87]
	v_mfma_f32_16x16x32_bf16 v[80:83], v[170:173], v[198:201], v[80:83]
	v_mfma_f32_16x16x32_bf16 v[68:71], v[162:165], v[214:217], v[68:71]
	v_mfma_f32_16x16x32_bf16 v[64:67], v[170:173], v[214:217], v[64:67]
	v_mfma_f32_16x16x32_bf16 v[116:119], v[166:169], v[186:189], v[116:119]
	v_mfma_f32_16x16x32_bf16 v[112:115], v[174:177], v[186:189], v[112:115]
	v_mfma_f32_16x16x32_bf16 v[100:103], v[166:169], v[194:197], v[100:103]
	v_mfma_f32_16x16x32_bf16 v[96:99], v[174:177], v[194:197], v[96:99]
	v_mfma_f32_16x16x32_bf16 v[84:87], v[166:169], v[210:213], v[84:87]
	v_mfma_f32_16x16x32_bf16 v[80:83], v[174:177], v[210:213], v[80:83]
	v_mfma_f32_16x16x32_bf16 v[68:71], v[166:169], v[218:221], v[68:71]
	v_mfma_f32_16x16x32_bf16 v[64:67], v[174:177], v[218:221], v[64:67]
	s_setprio 0
	s_barrier
	s_mov_b64 s[2:3], s[50:51]
	s_add_i32 s75, s66, s33
	ds_read_b128 v[178:181], v206 offset:16384
	ds_read_b128 v[186:189], v206 offset:17408
	ds_read_b128 v[190:193], v206 offset:18432
	ds_read_b128 v[194:197], v206 offset:19456
	ds_read_b128 v[198:201], v206 offset:20480
	ds_read_b128 v[210:213], v206 offset:21504
	ds_read_b128 v[214:217], v206 offset:22528
	ds_read_b128 v[218:221], v206 offset:23552
	s_mov_b32 m0, s75
	s_nop 0
	global_load_lds_dwordx4 v146, s[2:3]
	s_add_i32 m0, s75, 0x2000
	s_nop 0
	global_load_lds_dwordx4 v150, s[2:3]
	s_add_u32 s2, s50, 0x20000
	s_addc_u32 s3, s51, 0
	s_add_i32 s75, s67, s33
	s_mov_b32 m0, s75
	s_nop 0
	global_load_lds_dwordx4 v146, s[2:3]
	s_add_i32 m0, s75, 0x2000
	s_nop 0
	global_load_lds_dwordx4 v150, s[2:3]
	s_mov_b64 s[2:3], s[52:53]
	s_mov_b32 m0, s45
	s_nop 0
	global_load_lds_dwordx4 v144, s[2:3]
	s_mov_b32 m0, s47
	s_nop 0
	global_load_lds_dwordx4 v148, s[2:3]
	s_waitcnt vmcnt(8)
	s_waitcnt lgkmcnt(0)
	s_barrier
	s_setprio 1
	v_mfma_f32_16x16x32_bf16 v[60:63], v[128:131], v[178:181], v[60:63]
	v_mfma_f32_16x16x32_bf16 v[56:59], v[136:139], v[178:181], v[56:59]
	v_mfma_f32_16x16x32_bf16 v[44:47], v[128:131], v[190:193], v[44:47]
	v_mfma_f32_16x16x32_bf16 v[40:43], v[136:139], v[190:193], v[40:43]
	v_mfma_f32_16x16x32_bf16 v[28:31], v[128:131], v[198:201], v[28:31]
	v_mfma_f32_16x16x32_bf16 v[24:27], v[136:139], v[198:201], v[24:27]
	v_mfma_f32_16x16x32_bf16 v[12:15], v[128:131], v[214:217], v[12:15]
	v_mfma_f32_16x16x32_bf16 v[8:11], v[136:139], v[214:217], v[8:11]
	v_mfma_f32_16x16x32_bf16 v[60:63], v[132:135], v[186:189], v[60:63]
	v_mfma_f32_16x16x32_bf16 v[56:59], v[140:143], v[186:189], v[56:59]
	v_mfma_f32_16x16x32_bf16 v[44:47], v[132:135], v[194:197], v[44:47]
	v_mfma_f32_16x16x32_bf16 v[40:43], v[140:143], v[194:197], v[40:43]
	v_mfma_f32_16x16x32_bf16 v[28:31], v[132:135], v[210:213], v[28:31]
	v_mfma_f32_16x16x32_bf16 v[24:27], v[140:143], v[210:213], v[24:27]
	v_mfma_f32_16x16x32_bf16 v[12:15], v[132:135], v[218:221], v[12:15]
	v_mfma_f32_16x16x32_bf16 v[8:11], v[140:143], v[218:221], v[8:11]
	v_mfma_f32_16x16x32_bf16 v[52:55], v[162:165], v[178:181], v[52:55]
	v_mfma_f32_16x16x32_bf16 v[48:51], v[170:173], v[178:181], v[48:51]
	v_mfma_f32_16x16x32_bf16 v[36:39], v[162:165], v[190:193], v[36:39]
	v_mfma_f32_16x16x32_bf16 v[32:35], v[170:173], v[190:193], v[32:35]
	v_mfma_f32_16x16x32_bf16 v[20:23], v[162:165], v[198:201], v[20:23]
	v_mfma_f32_16x16x32_bf16 v[16:19], v[170:173], v[198:201], v[16:19]
	v_mfma_f32_16x16x32_bf16 v[4:7], v[162:165], v[214:217], v[4:7]
	v_mfma_f32_16x16x32_bf16 v[0:3], v[170:173], v[214:217], v[0:3]
	v_mfma_f32_16x16x32_bf16 v[52:55], v[166:169], v[186:189], v[52:55]
	v_mfma_f32_16x16x32_bf16 v[48:51], v[174:177], v[186:189], v[48:51]
	v_mfma_f32_16x16x32_bf16 v[36:39], v[166:169], v[194:197], v[36:39]
	v_mfma_f32_16x16x32_bf16 v[32:35], v[174:177], v[194:197], v[32:35]
	v_mfma_f32_16x16x32_bf16 v[20:23], v[166:169], v[210:213], v[20:23]
	v_mfma_f32_16x16x32_bf16 v[16:19], v[174:177], v[210:213], v[16:19]
	v_mfma_f32_16x16x32_bf16 v[4:7], v[166:169], v[218:221], v[4:7]
	v_mfma_f32_16x16x32_bf16 v[0:3], v[174:177], v[218:221], v[0:3]
	s_setprio 0
	s_barrier
; #define PG8_STAGE(bufoff, gbase, voff) do { unsigned long long _gb = (unsigned long long)(gbase); asm volatile("" : "+s"(_gb)); _Pragma("unroll") for (int _i = 0; _i < 2; ++_i) \
;         __builtin_amdgcn_global_load_lds((const GAS unsigned*)((const GAS char*)_gb + (voff)[_i]), (LAS unsigned*)(lds + (bufoff) + ldsw + _i * 8192), 16, 0, 0); } while (0)
; #define PG8_LDA(dst, b, h) do { _Pragma("unroll") for (int m = 0; m < 4; ++m) _Pragma("unroll") for (int k = 0; k < 2; ++k) dst[m][k] = *(const LAS bf16x8*)(lds + PG8_SA(b, h) + aoff + m * 2048 + k * 1024); } while (0)
; #define PG8_LDB(dst, b, h) do { _Pragma("unroll") for (int n = 0; n < 2; ++n) _Pragma("unroll") for (int k = 0; k < 2; ++k) dst[n][k] = *(const LAS bf16x8*)(lds + PG8_SB(b, h) + boff + n * 2048 + k * 1024); } while (0)
; #define PG8_MMA(ai, bj, At, Bt) do { __builtin_amdgcn_s_setprio(1); _Pragma("unroll") for (int m = 0; m < 4; ++m) _Pragma("unroll") for (int n = 0; n < 2; ++n) _Pragma("unroll") for (int k = 0; k < 2; ++k) \
;         acc[ai][bj][m][n] = __builtin_amdgcn_mfma_f32_16x16x32_bf16(Bt[n][k], At[m][k], acc[ai][bj][m][n], 0, 0, 0); __builtin_amdgcn_s_setprio(0); } while (0)
; #define PG8_WAIT_V(n) asm volatile("s_waitcnt vmcnt(" #n ")" ::: "memory")
; #define PG8_WAIT_L(n) asm volatile("s_waitcnt lgkmcnt(" #n ")" ::: "memory")
; #define PG8_BAR __builtin_amdgcn_s_barrier()
; #define PG8_SCHED __builtin_amdgcn_sched_barrier(0)
; template <class Epi, bool ALIGN_EPI>
; __device__ __forceinline__ void gemm_phase(LAS unsigned char* lds, const Gemm g, const StaticOrder& S, const Epi& E, const int wid) {
;     ...
;             PG8_LDB(B0, 1, 0); PG8_LDB(B1, 1, 1); PG8_SCHED; PG8_LDA(At, 1, 0); PG8_STAGE(PG8_SA(0, 1), a2 + hstep, voffA);
;             PG8_WAIT_V(8); PG8_WAIT_L(0); PG8_BAR; PG8_MMA(0, 0, At, B0); PG8_MMA(0, 1, At, B1); PG8_BAR; PG8_SCHED;
;             PG8_LDA(At, 1, 1); PG8_STAGE(PG8_SB(1, 0), b3, voffB); PG8_STAGE(PG8_SB(1, 1), b3 + hstepB, voffB); PG8_STAGE(PG8_SA(1, 0), a3, voffA);
;             PG8_WAIT_V(8); PG8_WAIT_L(0); PG8_BAR; PG8_MMA(1, 0, At, B0); PG8_MMA(1, 1, At, B1); PG8_BAR; PG8_SCHED;
;         }
	s_add_i32 s75, 0, 0x18000
	s_add_i32 s76, 0, 0x1c000
	v_add_u32_e32 v140, s75, v203
	v_add_u32_e32 v152, s76, v203
	ds_read_b128 v[128:131], v140
	ds_read_b128 v[132:135], v140 offset:1024
	ds_read_b128 v[136:139], v140 offset:2048
	ds_read_b128 v[140:143], v140 offset:3072
	ds_read_b128 v[162:165], v152
	ds_read_b128 v[166:169], v152 offset:1024
	ds_read_b128 v[170:173], v152 offset:2048
	ds_read_b128 v[174:177], v152 offset:3072
	s_add_u32 s2, s52, 0x80000
	s_addc_u32 s3, s53, 0
	s_mov_b32 m0, s57
	ds_read_b128 v[178:181], v206 offset:32768
	ds_read_b128 v[186:189], v206 offset:33792
	ds_read_b128 v[190:193], v206 offset:34816
	ds_read_b128 v[194:197], v206 offset:35840
	ds_read_b128 v[198:201], v206 offset:36864
	ds_read_b128 v[210:213], v206 offset:37888
	ds_read_b128 v[214:217], v206 offset:38912
	ds_read_b128 v[218:221], v206 offset:39936
	s_nop 0
	global_load_lds_dwordx4 v144, s[2:3]
	s_mov_b32 m0, s58
	s_nop 0
	global_load_lds_dwordx4 v148, s[2:3]
	s_waitcnt vmcnt(8)
	s_waitcnt lgkmcnt(0)
	s_barrier
	s_setprio 1
	v_mfma_f32_16x16x32_bf16 v[124:127], v[128:131], v[178:181], v[124:127]
	v_mfma_f32_16x16x32_bf16 v[120:123], v[136:139], v[178:181], v[120:123]
	v_mfma_f32_16x16x32_bf16 v[108:111], v[128:131], v[190:193], v[108:111]
	v_mfma_f32_16x16x32_bf16 v[104:107], v[136:139], v[190:193], v[104:107]
	v_mfma_f32_16x16x32_bf16 v[92:95], v[128:131], v[198:201], v[92:95]
	v_mfma_f32_16x16x32_bf16 v[88:91], v[136:139], v[198:201], v[88:91]
	v_mfma_f32_16x16x32_bf16 v[76:79], v[128:131], v[214:217], v[76:79]
	v_mfma_f32_16x16x32_bf16 v[72:75], v[136:139], v[214:217], v[72:75]
	v_mfma_f32_16x16x32_bf16 v[124:127], v[132:135], v[186:189], v[124:127]
	v_mfma_f32_16x16x32_bf16 v[120:123], v[140:143], v[186:189], v[120:123]
	v_mfma_f32_16x16x32_bf16 v[108:111], v[132:135], v[194:197], v[108:111]
	v_mfma_f32_16x16x32_bf16 v[104:107], v[140:143], v[194:197], v[104:107]
	v_mfma_f32_16x16x32_bf16 v[92:95], v[132:135], v[210:213], v[92:95]
	v_mfma_f32_16x16x32_bf16 v[88:91], v[140:143], v[210:213], v[88:91]
	v_mfma_f32_16x16x32_bf16 v[76:79], v[132:135], v[218:221], v[76:79]
	v_mfma_f32_16x16x32_bf16 v[72:75], v[140:143], v[218:221], v[72:75]
	v_mfma_f32_16x16x32_bf16 v[116:119], v[162:165], v[178:181], v[116:119]
	v_mfma_f32_16x16x32_bf16 v[112:115], v[170:173], v[178:181], v[112:115]
	v_mfma_f32_16x16x32_bf16 v[100:103], v[162:165], v[190:193], v[100:103]
	v_mfma_f32_16x16x32_bf16 v[96:99], v[170:173], v[190:193], v[96:99]
	v_mfma_f32_16x16x32_bf16 v[84:87], v[162:165], v[198:201], v[84:87]
	v_mfma_f32_16x16x32_bf16 v[80:83], v[170:173], v[198:201], v[80:83]
	v_mfma_f32_16x16x32_bf16 v[68:71], v[162:165], v[214:217], v[68:71]
	v_mfma_f32_16x16x32_bf16 v[64:67], v[170:173], v[214:217], v[64:67]
	v_mfma_f32_16x16x32_bf16 v[116:119], v[166:169], v[186:189], v[116:119]
	v_mfma_f32_16x16x32_bf16 v[112:115], v[174:177], v[186:189], v[112:115]
	v_mfma_f32_16x16x32_bf16 v[100:103], v[166:169], v[194:197], v[100:103]
	v_mfma_f32_16x16x32_bf16 v[96:99], v[174:177], v[194:197], v[96:99]
	v_mfma_f32_16x16x32_bf16 v[84:87], v[166:169], v[210:213], v[84:87]
	v_mfma_f32_16x16x32_bf16 v[80:83], v[174:177], v[210:213], v[80:83]
	v_mfma_f32_16x16x32_bf16 v[68:71], v[166:169], v[218:221], v[68:71]
	v_mfma_f32_16x16x32_bf16 v[64:67], v[174:177], v[218:221], v[64:67]
	s_setprio 0
	s_barrier
	s_add_u32 s2, s50, 0x80
	s_addc_u32 s3, s51, 0
	s_add_i32 s52, s75, s33
	ds_read_b128 v[178:181], v206 offset:49152
	ds_read_b128 v[186:189], v206 offset:50176
	ds_read_b128 v[190:193], v206 offset:51200
	ds_read_b128 v[194:197], v206 offset:52224
	ds_read_b128 v[198:201], v206 offset:53248
	ds_read_b128 v[210:213], v206 offset:54272
	ds_read_b128 v[214:217], v206 offset:55296
	ds_read_b128 v[218:221], v206 offset:56320
	s_mov_b32 m0, s52
	s_nop 0
	global_load_lds_dwordx4 v146, s[2:3]
	s_add_i32 m0, s52, 0x2000
	s_nop 0
	global_load_lds_dwordx4 v150, s[2:3]
	s_add_u32 s2, s50, 0x20080
	s_addc_u32 s3, s51, 0
	s_add_i32 s50, s76, s33
	s_mov_b32 m0, s50
	s_nop 0
	global_load_lds_dwordx4 v146, s[2:3]
	s_add_i32 m0, s50, 0x2000
	s_nop 0
	global_load_lds_dwordx4 v150, s[2:3]
	s_mov_b32 m0, s63
	s_nop 0
	global_load_lds_dwordx4 v144, s[48:49]
	s_mov_b32 m0, s64
	s_nop 0
	global_load_lds_dwordx4 v148, s[48:49]
	s_waitcnt vmcnt(8)
	s_waitcnt lgkmcnt(0)
	s_barrier
	s_setprio 1
	v_mfma_f32_16x16x32_bf16 v[60:63], v[128:131], v[178:181], v[60:63]
	v_mfma_f32_16x16x32_bf16 v[56:59], v[136:139], v[178:181], v[56:59]
	v_mfma_f32_16x16x32_bf16 v[44:47], v[128:131], v[190:193], v[44:47]
	v_mfma_f32_16x16x32_bf16 v[40:43], v[136:139], v[190:193], v[40:43]
	v_mfma_f32_16x16x32_bf16 v[28:31], v[128:131], v[198:201], v[28:31]
	v_mfma_f32_16x16x32_bf16 v[24:27], v[136:139], v[198:201], v[24:27]
	v_mfma_f32_16x16x32_bf16 v[12:15], v[128:131], v[214:217], v[12:15]
	v_mfma_f32_16x16x32_bf16 v[8:11], v[136:139], v[214:217], v[8:11]
	v_mfma_f32_16x16x32_bf16 v[60:63], v[132:135], v[186:189], v[60:63]
	v_mfma_f32_16x16x32_bf16 v[56:59], v[140:143], v[186:189], v[56:59]
	v_mfma_f32_16x16x32_bf16 v[44:47], v[132:135], v[194:197], v[44:47]
	v_mfma_f32_16x16x32_bf16 v[40:43], v[140:143], v[194:197], v[40:43]
	v_mfma_f32_16x16x32_bf16 v[28:31], v[132:135], v[210:213], v[28:31]
	v_mfma_f32_16x16x32_bf16 v[24:27], v[140:143], v[210:213], v[24:27]
	v_mfma_f32_16x16x32_bf16 v[12:15], v[132:135], v[218:221], v[12:15]
	v_mfma_f32_16x16x32_bf16 v[8:11], v[140:143], v[218:221], v[8:11]
	v_mfma_f32_16x16x32_bf16 v[52:55], v[162:165], v[178:181], v[52:55]
	v_mfma_f32_16x16x32_bf16 v[48:51], v[170:173], v[178:181], v[48:51]
	v_mfma_f32_16x16x32_bf16 v[36:39], v[162:165], v[190:193], v[36:39]
	v_mfma_f32_16x16x32_bf16 v[32:35], v[170:173], v[190:193], v[32:35]
	v_mfma_f32_16x16x32_bf16 v[20:23], v[162:165], v[198:201], v[20:23]
	v_mfma_f32_16x16x32_bf16 v[16:19], v[170:173], v[198:201], v[16:19]
	v_mfma_f32_16x16x32_bf16 v[4:7], v[162:165], v[214:217], v[4:7]
	v_mfma_f32_16x16x32_bf16 v[0:3], v[170:173], v[214:217], v[0:3]
	v_mfma_f32_16x16x32_bf16 v[52:55], v[166:169], v[186:189], v[52:55]
	v_mfma_f32_16x16x32_bf16 v[48:51], v[174:177], v[186:189], v[48:51]
	v_mfma_f32_16x16x32_bf16 v[36:39], v[166:169], v[194:197], v[36:39]
	v_mfma_f32_16x16x32_bf16 v[32:35], v[174:177], v[194:197], v[32:35]
	v_mfma_f32_16x16x32_bf16 v[20:23], v[166:169], v[210:213], v[20:23]
	v_mfma_f32_16x16x32_bf16 v[16:19], v[174:177], v[210:213], v[16:19]
	v_mfma_f32_16x16x32_bf16 v[4:7], v[166:169], v[218:221], v[4:7]
	v_mfma_f32_16x16x32_bf16 v[0:3], v[174:177], v[218:221], v[0:3]
	s_setprio 0
	s_barrier
	s_add_i32 s74, s74, 2
	s_add_u32 s72, s72, 0x100
	s_addc_u32 s73, s73, 0
	s_cmp_gt_u32 s74, 29
	s_mov_b64 s[2:3], s[6:7]
	s_cbranch_scc0 .LBB0_105
	s_and_b64 vcc, exec, s[84:85]
	s_cbranch_vccz .LBB0_108
	s_barrier
